# baseline (speedup 1.0000x reference)
; __device__ __forceinline__ unsigned pk2(float lo, float hi) { return f2bf(lo) | (f2bf(hi) << 16); }
; __global__ void __launch_bounds__(NWAVES * 64) fwd_mega(Params p) {
;     ...
;         for (int m0 = 2 * gw; m0 < M; m0 += 2 * NGW) {
;             f32x4 v[2][4]; float s[2];
; #pragma unroll
;             for (int rr = 0; rr < 2; ++rr) { const f32x4* xr = (const f32x4*)(p.x + (size_t)(m0 + rr) * D) + lane;
; #pragma unroll
;                 for (int j = 0; j < 4; ++j) v[rr][j] = xr[64 * j]; }
; #pragma unroll
;             for (int rr = 0; rr < 2; ++rr) { const int m = m0 + rr; float sl = 0.f;
; #pragma unroll
;                 for (int j = 0; j < 4; ++j) sl += (v[rr][j].x * v[rr][j].x + v[rr][j].y * v[rr][j].y) + (v[rr][j].z * v[rr][j].z + v[rr][j].w * v[rr][j].w);
;                 s[rr] = wave_sum(sl);
;                 v2u* o8 = (v2u*)(XB + (size_t)m * D) + lane;
; #pragma unroll
;                 for (int j = 0; j < 4; ++j) { v2u w; w.x = pk2(v[rr][j].x, v[rr][j].y); w.y = pk2(v[rr][j].z, v[rr][j].w); o8[64 * j] = w; }
;                 if (lane < 8) ssq[(size_t)lane * M + m] = (lane == 0) ? (unsigned long long)(s[rr] * 1048576.0f) : 0ull;
;                 if (lane < 8) { const float ang = (float)p.pos[m] * p.inv_freq[lane]; const double a = (double)ang; const double k = __builtin_rint(a * 0.15915494309189535);
;                     const float rf = (float)(a - k * 6.283185307179586); ((float*)(ws + WS_CS))[(size_t)m * 8 + lane] = __cosf(rf); ((float*)(ws + WS_SN))[(size_t)m * 8 + lane] = __sinf(rf); } }
.LBB0_100:
	s_and_saveexec_b64 s[98:99], s[0:1]
	global_load_dword v80, v34, s[10:11] offset:-4
	global_load_dword v81, v34, s[10:11]
	global_load_dword v82, v[18:19], off offset:144
	s_mov_b64 exec, s[98:99]
	global_load_dwordx4 v[30:33], v[24:25], off offset:-4096
	global_load_dwordx4 v[44:47], v[24:25], off offset:-3072
	global_load_dwordx4 v[48:51], v[24:25], off offset:-2048
	global_load_dwordx4 v[52:55], v[24:25], off offset:-1024
	global_load_dwordx4 v[14:17], v[24:25], off
	global_load_dwordx4 v[10:13], v[24:25], off offset:1024
	global_load_dwordx4 v[6:9], v[24:25], off offset:2048
	global_load_dwordx4 v[2:5], v[24:25], off offset:3072
	v_readlane_b32 s26, v254, 1
	v_readlane_b32 s27, v254, 2
	s_waitcnt vmcnt(7) lgkmcnt(0)
	v_mul_f32_e32 v35, v31, v31
	v_mul_f32_e32 v43, v33, v33
	s_waitcnt vmcnt(6)
	v_mul_f32_e32 v56, v45, v45
	v_mul_f32_e32 v57, v47, v47
	s_waitcnt vmcnt(5)
	v_mul_f32_e32 v58, v49, v49
	v_mul_f32_e32 v59, v51, v51
	v_fmac_f32_e32 v35, v30, v30
	v_fmac_f32_e32 v43, v32, v32
	v_fmac_f32_e32 v56, v44, v44
	v_fmac_f32_e32 v57, v46, v46
	s_waitcnt vmcnt(4)
	v_mul_f32_e32 v60, v53, v53
	v_mul_f32_e32 v61, v55, v55
	v_fmac_f32_e32 v58, v48, v48
	v_fmac_f32_e32 v59, v50, v50
	v_add_f32_e32 v35, v35, v43
	v_add_f32_e32 v43, v56, v57
	v_fmac_f32_e32 v60, v52, v52
	v_fmac_f32_e32 v61, v54, v54
	v_add_f32_e32 v56, v58, v59
	v_add_f32_e32 v35, v35, v43
	v_add_f32_e32 v57, v60, v61
	v_add_f32_e32 v35, v35, v56
	v_add_f32_e32 v35, v35, v57
	ds_bpermute_b32 v43, v37, v35
	v_bfe_u32 v62, v30, 16, 1
	v_bfe_u32 v64, v32, 16, 1
	v_lshl_add_u64 v[28:29], s[26:27], 0, v[20:21]
	v_bfe_u32 v63, v31, 16, 1
	s_waitcnt lgkmcnt(0)
	v_add_f32_e32 v35, v35, v43
	ds_bpermute_b32 v43, v38, v35
	v_bfe_u32 v65, v33, 16, 1
	v_bfe_u32 v66, v44, 16, 1
	v_bfe_u32 v68, v46, 16, 1
	v_bfe_u32 v70, v48, 16, 1
	s_waitcnt lgkmcnt(0)
	v_add_f32_e32 v35, v35, v43
	ds_bpermute_b32 v43, v39, v35
	v_bfe_u32 v72, v50, 16, 1
	v_add3_u32 v30, v30, v62, s7
	v_add3_u32 v32, v32, v64, s7
	v_add_co_u32_e32 v28, vcc, s28, v28
	s_waitcnt lgkmcnt(0)
	v_add_f32_e32 v35, v35, v43
	ds_bpermute_b32 v43, v40, v35
	v_bfe_u32 v67, v45, 16, 1
	v_bfe_u32 v69, v47, 16, 1
	v_bfe_u32 v71, v49, 16, 1
	v_bfe_u32 v73, v51, 16, 1
	s_waitcnt lgkmcnt(0)
	v_add_f32_e32 v35, v35, v43
	ds_bpermute_b32 v43, v41, v35
	v_bfe_u32 v74, v52, 16, 1
	v_bfe_u32 v76, v54, 16, 1
	v_add3_u32 v31, v31, v63, s7
	v_add3_u32 v33, v33, v65, s7
	s_waitcnt lgkmcnt(0)
	v_add_f32_e32 v35, v35, v43
	ds_bpermute_b32 v43, v42, v35
	v_add3_u32 v44, v44, v66, s7
	v_add3_u32 v46, v46, v68, s7
	v_add3_u32 v48, v48, v70, s7
	v_add3_u32 v50, v50, v72, s7
	v_lshrrev_b32_e32 v30, 16, v30
	v_lshrrev_b32_e32 v32, 16, v32
	v_addc_co_u32_e32 v29, vcc, 0, v29, vcc
	v_bfe_u32 v75, v53, 16, 1
	v_bfe_u32 v77, v55, 16, 1
	v_add3_u32 v45, v45, v67, s7
	v_add3_u32 v47, v47, v69, s7
	v_add3_u32 v49, v49, v71, s7
	v_add3_u32 v51, v51, v73, s7
	v_add3_u32 v52, v52, v74, s7
	v_add3_u32 v54, v54, v76, s7
	v_lshrrev_b32_e32 v44, 16, v44
	v_lshrrev_b32_e32 v46, 16, v46
	v_lshrrev_b32_e32 v48, 16, v48
	v_lshrrev_b32_e32 v50, 16, v50
	v_and_or_b32 v30, v31, s13, v30
	v_and_or_b32 v31, v33, s13, v32
	v_add3_u32 v53, v53, v75, s7
	v_lshrrev_b32_e32 v52, 16, v52
	v_lshrrev_b32_e32 v54, 16, v54
	v_and_or_b32 v32, v45, s13, v44
	v_and_or_b32 v33, v47, s13, v46
	v_and_or_b32 v44, v49, s13, v48
	v_and_or_b32 v45, v51, s13, v50
	global_store_dwordx2 v[28:29], v[30:31], off
	global_store_dwordx2 v[28:29], v[32:33], off offset:512
	global_store_dwordx2 v[28:29], v[44:45], off offset:1024
	v_add3_u32 v30, v55, v77, s7
	v_and_or_b32 v46, v53, s13, v52
	v_and_or_b32 v47, v30, s13, v54
	v_lshl_add_u64 v[30:31], s[26:27], 0, v[26:27]
	v_lshl_add_u64 v[32:33], s[26:27], 0, v[22:23]
	global_store_dwordx2 v[28:29], v[46:47], off offset:1536
	s_and_saveexec_b64 s[26:27], s[0:1]
	s_cbranch_execz .LBB0_102
	s_waitcnt lgkmcnt(0)
	v_add_f32_e32 v35, v35, v43
	v_mul_f32_e32 v35, 0x49800000, v35
	v_trunc_f32_e32 v35, v35
	v_mul_f32_e32 v43, 0x2f800000, v35
	v_floor_f32_e32 v43, v43
	v_cvt_u32_f32_e32 v49, v43
	v_fmac_f32_e32 v35, 0xcf800000, v43
	v_cvt_u32_f32_e32 v35, v35
	v_add_co_u32_e32 v44, vcc, 0x16500000, v32
	v_cndmask_b32_e64 v49, 0, v49, s[4:5]
	s_nop 0
	v_addc_co_u32_e32 v45, vcc, 0, v33, vcc
	v_add_co_u32_e32 v46, vcc, 0x16600000, v32
	v_cvt_f32_i32_e32 v48, v80
	v_addc_co_u32_e32 v47, vcc, 0, v33, vcc
	v_mul_f32_e32 v43, v82, v48
	v_cvt_f64_f32_e32 v[50:51], v43
	v_mul_f64 v[52:53], v[50:51], s[22:23]
	v_rndne_f64_e32 v[52:53], v[52:53]
	v_fmac_f64_e32 v[50:51], s[24:25], v[52:53]
	v_cvt_f32_f64_e32 v43, v[50:51]
	v_mul_f32_e32 v43, 0.15915494, v43
	v_cos_f32_e32 v50, v43
	v_sin_f32_e32 v43, v43
	v_cndmask_b32_e64 v48, 0, v35, s[4:5]
	global_store_dwordx2 v[30:31], v[48:49], off
	global_store_dword v[44:45], v50, off
	global_store_dword v[46:47], v43, off
; __device__ __forceinline__ unsigned pk2(float lo, float hi) { return f2bf(lo) | (f2bf(hi) << 16); }
; __global__ void __launch_bounds__(NWAVES * 64) fwd_mega(Params p) {
;     ...
;             for (int rr = 0; rr < 2; ++rr) { const int m = m0 + rr; float sl = 0.f;
; #pragma unroll
;                 for (int j = 0; j < 4; ++j) sl += (v[rr][j].x * v[rr][j].x + v[rr][j].y * v[rr][j].y) + (v[rr][j].z * v[rr][j].z + v[rr][j].w * v[rr][j].w);
;                 s[rr] = wave_sum(sl);
;                 v2u* o8 = (v2u*)(XB + (size_t)m * D) + lane;
; #pragma unroll
;                 for (int j = 0; j < 4; ++j) { v2u w; w.x = pk2(v[rr][j].x, v[rr][j].y); w.y = pk2(v[rr][j].z, v[rr][j].w); o8[64 * j] = w; }
;                 if (lane < 8) ssq[(size_t)lane * M + m] = (lane == 0) ? (unsigned long long)(s[rr] * 1048576.0f) : 0ull;
;                 if (lane < 8) { const float ang = (float)p.pos[m] * p.inv_freq[lane]; const double a = (double)ang; const double k = __builtin_rint(a * 0.15915494309189535);
;                     const float rf = (float)(a - k * 6.283185307179586); ((float*)(ws + WS_CS))[(size_t)m * 8 + lane] = __cosf(rf); ((float*)(ws + WS_SN))[(size_t)m * 8 + lane] = __sinf(rf); } }
.LBB0_102:
	s_or_b64 exec, exec, s[26:27]
	s_waitcnt vmcnt(7)
	v_mul_f32_e32 v35, v15, v15
	s_waitcnt lgkmcnt(0)
	v_mul_f32_e32 v43, v17, v17
	v_fmac_f32_e32 v35, v14, v14
	v_fmac_f32_e32 v43, v16, v16
	v_add_f32_e32 v35, v35, v43
	s_waitcnt vmcnt(6)
	v_mul_f32_e32 v43, v11, v11
	v_mul_f32_e32 v44, v13, v13
	v_fmac_f32_e32 v43, v10, v10
	v_fmac_f32_e32 v44, v12, v12
	v_add_f32_e32 v43, v43, v44
	v_add_f32_e32 v35, v35, v43
	s_waitcnt vmcnt(5)
	v_mul_f32_e32 v43, v7, v7
	v_mul_f32_e32 v44, v9, v9
	v_fmac_f32_e32 v43, v6, v6
	v_fmac_f32_e32 v44, v8, v8
	v_add_f32_e32 v43, v43, v44
	v_add_f32_e32 v35, v35, v43
	s_waitcnt vmcnt(4)
	v_mul_f32_e32 v43, v3, v3
	v_mul_f32_e32 v44, v5, v5
	v_fmac_f32_e32 v43, v2, v2
	v_fmac_f32_e32 v44, v4, v4
	v_add_f32_e32 v43, v43, v44
	v_add_f32_e32 v35, v35, v43
	ds_bpermute_b32 v43, v37, v35
	v_bfe_u32 v44, v14, 16, 1
	v_add3_u32 v14, v14, v44, s7
	v_lshrrev_b32_e32 v44, 16, v14
	s_waitcnt lgkmcnt(0)
	v_add_f32_e32 v35, v35, v43
	ds_bpermute_b32 v43, v38, v35
	s_waitcnt lgkmcnt(0)
	v_add_f32_e32 v35, v35, v43
	ds_bpermute_b32 v43, v39, v35
	s_waitcnt lgkmcnt(0)
	v_add_f32_e32 v35, v35, v43
	ds_bpermute_b32 v43, v40, v35
	s_waitcnt lgkmcnt(0)
	v_add_f32_e32 v35, v35, v43
	ds_bpermute_b32 v43, v41, v35
	s_waitcnt lgkmcnt(0)
	v_add_f32_e32 v14, v35, v43
	v_bfe_u32 v43, v15, 16, 1
	v_add3_u32 v15, v15, v43, s7
	v_and_or_b32 v44, v15, s13, v44
	v_bfe_u32 v15, v16, 16, 1
	v_add3_u32 v15, v16, v15, s7
	v_bfe_u32 v16, v17, 16, 1
	v_lshrrev_b32_e32 v15, 16, v15
	v_add3_u32 v16, v17, v16, s7
	v_and_or_b32 v45, v16, s13, v15
	v_bfe_u32 v15, v10, 16, 1
	v_add3_u32 v10, v10, v15, s7
	v_bfe_u32 v15, v11, 16, 1
	v_lshrrev_b32_e32 v10, 16, v10
	v_add3_u32 v11, v11, v15, s7
	v_and_or_b32 v10, v11, s13, v10
	v_bfe_u32 v11, v12, 16, 1
	v_add3_u32 v11, v12, v11, s7
	v_bfe_u32 v12, v13, 16, 1
	v_lshrrev_b32_e32 v11, 16, v11
	v_add3_u32 v12, v13, v12, s7
	v_and_or_b32 v11, v12, s13, v11
	global_store_dwordx2 v[28:29], v[10:11], off offset:2560
	v_bfe_u32 v10, v6, 16, 1
	v_add3_u32 v6, v6, v10, s7
	v_bfe_u32 v10, v7, 16, 1
	v_lshrrev_b32_e32 v6, 16, v6
	v_add3_u32 v7, v7, v10, s7
	v_and_or_b32 v6, v7, s13, v6
	v_bfe_u32 v7, v8, 16, 1
	v_add3_u32 v7, v8, v7, s7
	v_bfe_u32 v8, v9, 16, 1
	v_lshrrev_b32_e32 v7, 16, v7
	v_add3_u32 v8, v9, v8, s7
	v_and_or_b32 v7, v8, s13, v7
	global_store_dwordx2 v[28:29], v[6:7], off offset:3072
	v_bfe_u32 v6, v2, 16, 1
	v_add3_u32 v2, v2, v6, s7
	v_bfe_u32 v6, v3, 16, 1
	ds_bpermute_b32 v35, v42, v14
	v_lshrrev_b32_e32 v2, 16, v2
	v_add3_u32 v3, v3, v6, s7
	v_and_or_b32 v2, v3, s13, v2
	v_bfe_u32 v3, v4, 16, 1
	v_add3_u32 v3, v4, v3, s7
	v_bfe_u32 v4, v5, 16, 1
	v_lshrrev_b32_e32 v3, 16, v3
	v_add3_u32 v4, v5, v4, s7
	v_and_or_b32 v3, v4, s13, v3
	global_store_dwordx2 v[28:29], v[44:45], off offset:2048
	global_store_dwordx2 v[28:29], v[2:3], off offset:3584
	s_and_saveexec_b64 s[26:27], s[0:1]
	s_cbranch_execz .LBB0_99
	s_waitcnt lgkmcnt(0)
	v_add_f32_e32 v3, v14, v35
	v_mul_f32_e32 v5, 0x49800000, v3
	v_trunc_f32_e32 v7, v5
	v_mul_f32_e32 v9, 0x2f800000, v7
	v_floor_f32_e32 v9, v9
	v_cvt_u32_f32_e32 v10, v9
	v_fmac_f32_e32 v7, 0xcf800000, v9
	v_cvt_u32_f32_e32 v12, v7
	v_add_co_u32_e32 v2, vcc, 0x16500000, v32
	v_cndmask_b32_e64 v7, 0, v10, s[4:5]
	s_nop 0
	v_addc_co_u32_e32 v3, vcc, 0, v33, vcc
	v_add_co_u32_e32 v4, vcc, 0x16600000, v32
	v_cvt_f32_i32_e32 v6, v81
	v_addc_co_u32_e32 v5, vcc, 0, v33, vcc
	v_mul_f32_e32 v6, v82, v6
	v_cvt_f64_f32_e32 v[8:9], v6
	v_mul_f64 v[10:11], v[8:9], s[22:23]
	v_rndne_f64_e32 v[10:11], v[10:11]
	v_fmac_f64_e32 v[8:9], s[24:25], v[10:11]
	v_cvt_f32_f64_e32 v6, v[8:9]
	v_mul_f32_e32 v6, 0.15915494, v6
	v_cos_f32_e32 v8, v6
	v_sin_f32_e32 v9, v6
	v_cndmask_b32_e64 v6, 0, v12, s[4:5]
	global_store_dwordx2 v[30:31], v[6:7], off offset:8
	global_store_dword v[2:3], v8, off offset:32
	global_store_dword v[4:5], v9, off offset:32
	s_branch .LBB0_99

; #define LAS __attribute__((address_space(3)))
; __global__ void __launch_bounds__(NWAVES * 64) fwd_mega(Params p) {
;     extern __shared__ __attribute__((aligned(16))) unsigned char lds_raw[];
;     LAS unsigned char* lds = (LAS unsigned char*)lds_raw;
;     cg::grid_group grid = cg::this_grid();
;     const int wave = __builtin_amdgcn_readfirstlane((int)threadIdx.x >> 6);
	.amdhsa_kernel _Z8fwd_mega6Params
		.amdhsa_group_segment_fixed_size 0
		.amdhsa_private_segment_fixed_size 0
		.amdhsa_kernarg_size 448
		.amdhsa_user_sgpr_count 2
		.amdhsa_user_sgpr_dispatch_ptr 0
		.amdhsa_user_sgpr_queue_ptr 0
		.amdhsa_user_sgpr_kernarg_segment_ptr 1
		.amdhsa_user_sgpr_dispatch_id 0
		.amdhsa_user_sgpr_kernarg_preload_length 0
		.amdhsa_user_sgpr_kernarg_preload_offset 0
		.amdhsa_user_sgpr_private_segment_size 0
		.amdhsa_uses_dynamic_stack 0
		.amdhsa_enable_private_segment 0
		.amdhsa_system_sgpr_workgroup_id_x 1
		.amdhsa_system_sgpr_workgroup_id_y 0
		.amdhsa_system_sgpr_workgroup_id_z 0
		.amdhsa_system_sgpr_workgroup_info 0
		.amdhsa_system_vgpr_workitem_id 2
		.amdhsa_next_free_vgpr 256
		.amdhsa_next_free_sgpr 102
		.amdhsa_accum_offset 256
		.amdhsa_reserve_vcc 1
		.amdhsa_float_round_mode_32 0
		.amdhsa_float_round_mode_16_64 0
		.amdhsa_float_denorm_mode_32 3
		.amdhsa_float_denorm_mode_16_64 3
		.amdhsa_dx10_clamp 1
		.amdhsa_ieee_mode 1
		.amdhsa_fp16_overflow 0
		.amdhsa_tg_split 0
		.amdhsa_exception_fp_ieee_invalid_op 0
		.amdhsa_exception_fp_denorm_src 0
		.amdhsa_exception_fp_ieee_div_zero 0
		.amdhsa_exception_fp_ieee_overflow 0
		.amdhsa_exception_fp_ieee_underflow 0
		.amdhsa_exception_fp_ieee_inexact 0
		.amdhsa_exception_int_div_zero 0
	.end_amdhsa_kernel

; #define LAS __attribute__((address_space(3)))
; __global__ void __launch_bounds__(NWAVES * 64) fwd_mega(Params p) {
;     extern __shared__ __attribute__((aligned(16))) unsigned char lds_raw[];
;     LAS unsigned char* lds = (LAS unsigned char*)lds_raw;
;     cg::grid_group grid = cg::this_grid();
;     const int wave = __builtin_amdgcn_readfirstlane((int)threadIdx.x >> 6);
amdhsa.kernels:
  - .agpr_count:     0
    .args:
      - .offset:         0
        .size:           192
        .value_kind:     by_value
      - .offset:         192
        .size:           4
        .value_kind:     hidden_block_count_x
      - .offset:         196
        .size:           4
        .value_kind:     hidden_block_count_y
      - .offset:         200
        .size:           4
        .value_kind:     hidden_block_count_z
      - .offset:         204
        .size:           2
        .value_kind:     hidden_group_size_x
      - .offset:         206
        .size:           2
        .value_kind:     hidden_group_size_y
      - .offset:         208
        .size:           2
        .value_kind:     hidden_group_size_z
      - .offset:         210
        .size:           2
        .value_kind:     hidden_remainder_x
      - .offset:         212
        .size:           2
        .value_kind:     hidden_remainder_y
      - .offset:         214
        .size:           2
        .value_kind:     hidden_remainder_z
      - .offset:         232
        .size:           8
        .value_kind:     hidden_global_offset_x
      - .offset:         240
        .size:           8
        .value_kind:     hidden_global_offset_y
      - .offset:         248
        .size:           8
        .value_kind:     hidden_global_offset_z
      - .offset:         256
        .size:           2
        .value_kind:     hidden_grid_dims
      - .offset:         280
        .size:           8
        .value_kind:     hidden_multigrid_sync_arg
      - .offset:         312
        .size:           4
        .value_kind:     hidden_dynamic_lds_size
    .group_segment_fixed_size: 0
    .kernarg_segment_align: 8
    .kernarg_segment_size: 448
    .language:       OpenCL C
    .language_version:
      - 2
      - 0
    .max_flat_workgroup_size: 512
    .name:           _Z8fwd_mega6Params
    .private_segment_fixed_size: 0
    .sgpr_count:     108
    .sgpr_spill_count: 128
    .symbol:         _Z8fwd_mega6Params.kd
    .uniform_work_group_size: 1
    .uses_dynamic_stack: false
    .vgpr_count:     256
    .vgpr_spill_count: 0
    .wavefront_size: 64
